# hg scan unit: TOT exchange published before the previous unit RSm barrier, TOT barrier removed (4 to 3 barriers per unit)
# baseline (speedup 1.0000x reference)
; __device__ __forceinline__ void hg_block(ArgsP a_, int jl, unsigned char* smem) { const ArgsP a = a_;
;     ...
;     const int nunits = cb < 64 ? 33 : (1024 - (cb - 64) + (G - 64) - 1) / (G - 64);
;     const int c4 = (tid & 31) * 4, rg = tid >> 5, m = wid >> 1, hw = wid & 1, irow = 16 * m + fr;
;     f32x4 S[1][8]; f32x4 O[4];
;     f32x4 lf4[4]; u32x2 kk2[4], q2[4], v2[4]; u32x2 gpre[4];
;     if (tid < 64) GI[tid] = 0.f;
;     ...
;     if (nunits > 0) HG_LOAD(0);
;     const int ntot_ = cb < 64 ? nunits : nunits * REP_SMP;
.LBB0_388:
	v_and_b32_e32 v92, 15, v22
	s_andn2_b64 vcc, exec, s[46:47]
	s_cbranch_vccnz .LBB0_442
; __device__ __forceinline__ void hg_block(ArgsP a_, int jl, unsigned char* smem) { const ArgsP a = a_;
;     ...
;     const int c4 = (tid & 31) * 4, rg = tid >> 5, m = wid >> 1, hw = wid & 1, irow = 16 * m + fr;
;     f32x4 S[1][8]; f32x4 O[4];
;     f32x4 lf4[4]; u32x2 kk2[4], q2[4], v2[4]; u32x2 gpre[4];
;     if (tid < 64) GI[tid] = 0.f;
;     ...
;         { f32x4 pre = {0.f, 0.f, 0.f, 0.f}, gmid = pre, glast = pre;
; #pragma unroll
;           for (int k = 0; k < 16; ++k) { const f32x4 t = *(const f32x4*)(TOT + k * 128 + c4); if (k < rg) pre = pre + t; if (k < 8) gmid = gmid + t; glast = glast + t; }
	v_readlane_b32 s46, v254, 62
	v_readlane_b32 s47, v254, 63
	s_mov_b32 s60, s46
	s_mov_b32 s61, s12
	s_lshl_b64 s[46:47], s[60:61], 12
	s_add_u32 s44, s44, 0x12000000
	v_writelane_b32 v255, s44, 8
	s_addc_u32 s44, s45, 0
	s_add_u32 s48, s42, s46
	v_writelane_b32 v255, s44, 9
	s_addc_u32 s49, s43, s47
	s_lshl_b64 s[42:43], s[60:61], 10
	v_writelane_b32 v255, s42, 10
	v_lshlrev_b32_e32 v26, 2, v93
	s_sub_i32 s59, s50, 64
	v_writelane_b32 v255, s43, 11
	v_readlane_b32 s42, v254, 38
	v_readlane_b32 s50, v254, 41
	v_ashrrev_i32_e32 v29, 7, v22
	v_lshl_add_u32 v27, v25, 2, s42
	v_readlane_b32 s42, v254, 39
	v_lshlrev_b32_e32 v32, 1, v25
	v_lshlrev_b32_e32 v20, 2, v24
	v_add_u32_e32 v135, s42, v26
	v_cmp_gt_u32_e64 s[42:43], 32, v22
	v_add_u32_e32 v137, s50, v26
	v_lshlrev_b32_e32 v26, 6, v25
	v_writelane_b32 v255, s42, 12
	v_cmp_le_i32_e64 s[44:45], v32, v29
	v_cmp_lt_i32_e64 s[46:47], v32, v29
	v_writelane_b32 v255, s43, 13
	s_add_i32 s42, 0, 0x20800
	v_lshlrev_b32_e32 v32, 4, v24
	v_lshlrev_b32_e32 v34, 5, v25
	v_lshlrev_b32_e32 v25, 7, v25
	v_lshl_or_b32 v31, v29, 4, v92
	v_add3_u32 v141, s42, v32, v25
	v_or_b32_e32 v25, v34, v20
	v_cmp_gt_i32_e64 s[62:63], v25, v31
	v_or_b32_e32 v35, v34, v92
	v_or_b32_e32 v34, 2, v25
	v_writelane_b32 v255, s62, 14
	v_ashrrev_i32_e32 v21, 6, v22
	v_lshlrev_b32_e32 v28, 4, v21
	v_writelane_b32 v255, s63, 15
	v_cmp_lt_i32_e64 s[62:63], v25, v31
	v_lshlrev_b32_e32 v21, 5, v21
	v_lshlrev_b32_e32 v30, 3, v24
	v_writelane_b32 v255, s62, 16
	v_readlane_b32 s43, v254, 36
	v_readlane_b32 s51, v254, 42
	v_writelane_b32 v255, s63, 17
	v_cmp_gt_i32_e64 s[62:63], v34, v31
	v_or_b32_e32 v34, 3, v25
	v_add3_u32 v21, s43, v21, v30
	v_writelane_b32 v255, s62, 18
	v_add_u32_e32 v33, s43, v32
	s_movk_i32 s43, 0x90
	v_writelane_b32 v255, s63, 19
	v_cmp_gt_i32_e64 s[62:63], v34, v31
	v_or_b32_e32 v34, 16, v25
	v_mul_lo_u32 v36, v31, s43
	v_writelane_b32 v255, s62, 20
	v_add_u32_e32 v36, s51, v36
	v_lshl_add_u32 v142, v25, 1, v36
	v_writelane_b32 v255, s63, 21
	v_cmp_gt_i32_e64 s[62:63], v34, v31
	s_movk_i32 s53, 0x110
	v_and_b32_e32 v22, 0xffffffc0, v22
	v_writelane_b32 v255, s62, 22
	v_lshl_add_u32 v138, v31, 2, s42
	v_mul_lo_u32 v29, v31, s53
	v_writelane_b32 v255, s63, 23
	v_cmp_lt_i32_e64 s[62:63], v34, v31
	v_or_b32_e32 v34, 18, v25
	v_or_b32_e32 v25, 19, v25
	v_writelane_b32 v255, s62, 24
	v_readlane_b32 s54, v254, 40
	v_lshl_add_u32 v16, v93, 1, 0
	v_writelane_b32 v255, s63, 25
	v_cmp_gt_i32_e64 s[62:63], v34, v31
	v_lshlrev_b32_e32 v136, 2, v23
	v_or_b32_e32 v18, v20, v28
	v_writelane_b32 v255, s62, 26
	s_ashr_i32 s57, s13, 3
	s_sub_i32 s55, s13, 64
	v_writelane_b32 v255, s63, 27
	v_cmp_gt_i32_e64 s[62:63], v25, v31
	v_add_u32_e32 v31, s50, v22
	v_or_b32_e32 v22, v28, v92
	v_writelane_b32 v255, s62, 28
	s_mov_b32 s50, s60
	v_mul_lo_u32 v22, v22, s43
	v_writelane_b32 v255, s63, 29
	v_cmp_eq_u32_e64 s[42:43], 0, v24
	v_writelane_b32 v254, s50, 62
	v_ashrrev_i32_e32 v19, 31, v18
	v_writelane_b32 v255, s42, 30
	v_writelane_b32 v254, s51, 63
	s_movk_i32 s50, 0x440
	v_writelane_b32 v255, s43, 31
	v_mad_u64_u32 v[106:107], s[50:51], v23, s50, v[16:17]
	v_readlane_b32 s42, v255, 4
	v_or_b32_e32 v107, 1, v136
	v_readlane_b32 s43, v255, 5
	v_mad_u64_u32 v[108:109], s[50:51], v107, s53, v[16:17]
	v_mul_u32_u24_e32 v16, 0x48, v93
	v_lshlrev_b64 v[96:97], 9, v[18:19]
	v_lshlrev_b32_e32 v18, 3, v23
	v_add3_u32 v144, 0, v22, v32
	v_or_b32_e32 v22, v26, v20
	s_and_b64 s[42:43], s[42:43], exec
	v_lshlrev_b32_e32 v16, 1, v16
	s_mov_b32 s42, 0x1300000
	v_add3_u32 v166, 0, v18, v16
	v_add3_u32 v167, s54, v18, v16
	v_lshlrev_b32_e32 v16, 2, v22
	s_cselect_b32 s52, s42, 0x1100000
	s_cselect_b32 s42, 7, 3
	v_lshl_add_u64 v[114:115], s[48:49], 0, v[16:17]
	s_add_i32 s48, s56, -1
	v_add3_u32 v139, 0, v29, v32
	v_or_b32_e32 v29, v26, v92
	v_mul_u32_u24_e32 v35, 0x110, v35
	v_writelane_b32 v255, s48, 32
	s_lshl_b32 s48, s52, 2
	v_lshlrev_b32_e32 v19, 9, v23
	v_mul_u32_u24_e32 v30, 0x110, v92
	v_add3_u32 v140, 0, v35, v32
	v_mul_u32_u24_e32 v35, 0x110, v29
	v_add_u32_e32 v25, s54, v32
	v_mul_u32_u24_e32 v29, 0x90, v29
	v_mul_u32_u24_e32 v28, 0x90, v92
	v_lshlrev_b32_e32 v145, 3, v134
	v_mov_b32_e32 v18, 0
	v_writelane_b32 v255, s48, 33
	s_mul_i32 s58, s57, 0x810
	v_add_u32_e32 v143, v36, v32
	s_mov_b32 s65, 0
	s_lshl_b64 s[42:43], s[60:61], s42
	v_cmp_lt_i32_e64 s[66:67], 0, v23
	v_cmp_lt_i32_e64 s[68:69], 1, v23
	v_cmp_lt_i32_e64 s[70:71], 2, v23
	v_cmp_lt_i32_e64 s[72:73], 3, v23
	v_cmp_lt_i32_e64 s[74:75], 4, v23
	v_cmp_lt_i32_e64 s[76:77], 5, v23
	v_cmp_lt_i32_e64 s[78:79], 6, v23
	v_cmp_lt_i32_e64 s[80:81], 7, v23
	v_cmp_lt_i32_e64 s[82:83], 8, v23
	v_cmp_lt_i32_e64 s[84:85], 9, v23
	v_cmp_lt_i32_e64 s[86:87], 10, v23
	v_cmp_lt_i32_e64 s[88:89], 11, v23
	v_cmp_lt_i32_e64 s[90:91], 12, v23
	v_cmp_lt_i32_e64 s[92:93], 13, v23
	v_cmp_lt_i32_e64 s[94:95], 14, v23
	v_cmp_lt_i32_e64 s[96:97], 15, v23
	v_or_b32_e32 v109, 2, v136
	v_add_u32_e32 v147, 0x110, v108
	v_or_b32_e32 v164, 3, v136
	v_add_u32_e32 v165, 0x220, v108
	v_add_u32_e32 v168, v135, v19
	v_lshlrev_b32_e32 v116, 1, v20
	v_lshlrev_b32_e32 v118, 1, v26
	v_add_u32_e32 v169, v21, v30
	v_add_u32_e32 v170, v25, v29
	v_add_u32_e32 v171, v31, v32
	v_add_u32_e32 v172, v25, v28
	v_and_b32_e32 v202, 15, v186
	v_lshrrev_b32_e32 v202, 3, v202
	v_bfe_u32 v203, v186, 4, 2
	v_lshrrev_b32_e32 v204, 6, v186
	v_lshl_add_u32 v205, v204, 1, v202
	v_and_b32_e32 v205, 3, v205
	v_xor_b32_e32 v205, v203, v205
	v_sub_u32_e32 v205, v205, v203
	v_lshl_add_u32 v144, v205, 4, v144
	v_xor_b32_e32 v205, v203, v202
	v_sub_u32_e32 v205, v205, v203
	v_lshl_add_u32 v184, v205, 4, v170
	v_lshl_add_u32 v250, v205, 4, v172
	v_or_b32_e32 v205, 2, v202
	v_xor_b32_e32 v205, v203, v205
	v_sub_u32_e32 v205, v205, v203
	v_lshl_add_u32 v185, v205, 4, v170
	v_lshl_add_u32 v251, v205, 4, v172
	v_bfe_u32 v205, v186, 1, 2
	v_and_b32_e32 v204, 3, v204
	v_xor_b32_e32 v205, v204, v205
	v_sub_u32_e32 v205, v205, v204
	v_lshl_add_u32 v166, v205, 4, v166
	v_lshl_add_u32 v167, v205, 4, v167
	v_add_u32_e32 v173, v27, v145
	v_lshlrev_b32_e32 v122, 1, v22
	v_add_u32_e32 v174, v33, v35
	v_writelane_b32 v255, s55, 34
	s_mov_b32 s60, s55
	v_mov_b32_e32 v19, v18
	v_mov_b32_e32 v20, v18
	v_mov_b32_e32 v21, v18
	v_mov_b32_e32 v22, v18
	v_mov_b32_e32 v23, v18
	v_mov_b32_e32 v24, v18
	v_mov_b32_e32 v25, v18
	v_mov_b32_e32 v26, v18
	v_mov_b32_e32 v27, v18
	v_mov_b32_e32 v28, v18
	v_mov_b32_e32 v29, v18
	v_mov_b32_e32 v30, v18
	v_mov_b32_e32 v31, v18
	v_mov_b32_e32 v32, v18
	v_mov_b32_e32 v33, v18
	v_mov_b32_e32 v34, v18
	v_mov_b32_e32 v35, v18
	v_mov_b32_e32 v36, v18
	v_mov_b32_e32 v37, v18
	v_mov_b32_e32 v38, v18
	v_mov_b32_e32 v39, v18
	v_mov_b32_e32 v40, v18
	v_mov_b32_e32 v41, v18
	v_mov_b32_e32 v42, v18
	v_mov_b32_e32 v43, v18
	v_mov_b32_e32 v44, v18
	v_mov_b32_e32 v45, v18
	v_mov_b32_e32 v46, v18
	v_mov_b32_e32 v47, v18
	v_mov_b32_e32 v48, v18
	v_mov_b32_e32 v49, v18
	s_mov_b32 s99, 1
	s_nop 0
	v_writelane_b32 v255, s99, 41
	s_branch .LBB0_391

; __device__ __forceinline__ void hg_block(ArgsP a_, int jl, unsigned char* smem) { const ArgsP a = a_;
;     ...
;         { f32x4 run = {0.f, 0.f, 0.f, 0.f};
; #pragma unroll
;           for (int r = 0; r < 4; ++r) { run = run + lf4[r]; cs[r] = run; }
;           *(f32x4*)(TOT + rg * 128 + c4) = run; }
;         __syncthreads();
;         { f32x4 pre = {0.f, 0.f, 0.f, 0.f}, gmid = pre, glast = pre;
; #pragma unroll
;           for (int k = 0; k < 16; ++k) { const f32x4 t = *(const f32x4*)(TOT + k * 128 + c4); if (k < rg) pre = pre + t; if (k < 8) gmid = gmid + t; glast = glast + t; }
;           f32x4 Emid, Elm;
; #pragma unroll
;           for (int e = 0; e < 4; ++e) { Emid[e] = __expf(gmid[e]); Elm[e] = __expf(glast[e] - gmid[e]); }
.Lhg_mask_done:
	v_pk_add_f32 v[62:63], v[2:3], 0 op_sel_hi:[1,0]
	v_pk_add_f32 v[64:65], v[0:1], 0 op_sel_hi:[1,0]
	v_pk_add_f32 v[58:59], v[62:63], v[6:7]
	v_pk_add_f32 v[60:61], v[64:65], v[4:5]
	v_pk_add_f32 v[54:55], v[58:59], v[10:11]
	v_pk_add_f32 v[56:57], v[60:61], v[8:9]
	v_pk_add_f32 v[52:53], v[54:55], v[14:15]
	v_pk_add_f32 v[50:51], v[56:57], v[12:13]
	v_readlane_b32 s99, v255, 41
	s_nop 1
	s_cmp_eq_u32 s99, 0
	s_cbranch_scc1 .Lhg_tot_done
	ds_write_b128 v168, v[50:53]
	s_waitcnt vmcnt(0) lgkmcnt(0)
	s_barrier
	s_mov_b32 s99, 0
	s_nop 0
	v_writelane_b32 v255, s99, 41
.Lhg_tot_done:
	ds_read_b128 v[202:205], v135
	ds_read_b128 v[206:209], v135 offset:512
	ds_read_b128 v[210:213], v135 offset:1024
	ds_read_b128 v[214:217], v135 offset:1536
	ds_read_b128 v[218:221], v135 offset:2048
	ds_read_b128 v[222:225], v135 offset:2560
	ds_read_b128 v[226:229], v135 offset:3072
	ds_read_b128 v[230:233], v135 offset:3584
	ds_read_b128 v[234:237], v135 offset:4096
	ds_read_b128 v[238:241], v135 offset:4608
	ds_read_b128 v[242:245], v135 offset:5120
	ds_read_b128 v[246:249], v135 offset:5632
	v_lshlrev_b32_e32 v175, 16, v78
	v_and_b32_e32 v178, 0xffff0000, v79
	s_mov_b32 s49, 0xffff0000
	s_waitcnt lgkmcnt(11)
	v_pk_add_f32 v[70:71], v[204:205], 0 op_sel_hi:[1,0]
	v_pk_add_f32 v[72:73], v[202:203], 0 op_sel_hi:[1,0]
	ds_read_b128 v[202:205], v135 offset:6144
	v_cndmask_b32_e64 v75, 0, v73, s[66:67]
	v_cndmask_b32_e64 v74, 0, v72, s[66:67]
	v_cndmask_b32_e64 v77, 0, v71, s[66:67]
	v_cndmask_b32_e64 v76, 0, v70, s[66:67]
	s_waitcnt lgkmcnt(11)
	v_pk_add_f32 v[126:127], v[206:207], v[74:75]
	v_pk_add_f32 v[128:129], v[208:209], v[76:77]
	v_pk_add_f32 v[70:71], v[70:71], v[208:209]
	v_pk_add_f32 v[72:73], v[72:73], v[206:207]
	ds_read_b128 v[206:209], v135 offset:6656
	v_cndmask_b32_e64 v75, v75, v127, s[68:69]
	v_cndmask_b32_e64 v74, v74, v126, s[68:69]
	v_cndmask_b32_e64 v77, v77, v129, s[68:69]
	v_cndmask_b32_e64 v76, v76, v128, s[68:69]
	s_waitcnt lgkmcnt(11)
	v_pk_add_f32 v[126:127], v[210:211], v[74:75]
	v_pk_add_f32 v[128:129], v[212:213], v[76:77]
	v_pk_add_f32 v[70:71], v[70:71], v[212:213]
	v_pk_add_f32 v[72:73], v[72:73], v[210:211]
	ds_read_b128 v[210:213], v135 offset:7168
	v_cndmask_b32_e64 v75, v75, v127, s[70:71]
	v_cndmask_b32_e64 v74, v74, v126, s[70:71]
	v_cndmask_b32_e64 v77, v77, v129, s[70:71]
	v_cndmask_b32_e64 v76, v76, v128, s[70:71]
	s_waitcnt lgkmcnt(11)
	v_pk_add_f32 v[126:127], v[214:215], v[74:75]
	v_pk_add_f32 v[128:129], v[216:217], v[76:77]
	v_pk_add_f32 v[70:71], v[70:71], v[216:217]
	v_pk_add_f32 v[72:73], v[72:73], v[214:215]
	ds_read_b128 v[214:217], v135 offset:7680
	v_cndmask_b32_e64 v75, v75, v127, s[72:73]
	v_cndmask_b32_e64 v74, v74, v126, s[72:73]
	v_cndmask_b32_e64 v77, v77, v129, s[72:73]
	v_cndmask_b32_e64 v76, v76, v128, s[72:73]
	s_waitcnt lgkmcnt(11)
	v_pk_add_f32 v[126:127], v[218:219], v[74:75]
	v_pk_add_f32 v[128:129], v[220:221], v[76:77]
	v_pk_add_f32 v[70:71], v[70:71], v[220:221]
	v_pk_add_f32 v[72:73], v[72:73], v[218:219]
	v_cndmask_b32_e64 v75, v75, v127, s[74:75]
	v_cndmask_b32_e64 v74, v74, v126, s[74:75]
	v_cndmask_b32_e64 v77, v77, v129, s[74:75]
	v_cndmask_b32_e64 v76, v76, v128, s[74:75]
	s_waitcnt lgkmcnt(10)
	v_pk_add_f32 v[126:127], v[222:223], v[74:75]
	v_pk_add_f32 v[128:129], v[224:225], v[76:77]
	v_pk_add_f32 v[70:71], v[70:71], v[224:225]
	v_pk_add_f32 v[72:73], v[72:73], v[222:223]
	v_cndmask_b32_e64 v75, v75, v127, s[76:77]
	v_cndmask_b32_e64 v74, v74, v126, s[76:77]
	v_cndmask_b32_e64 v77, v77, v129, s[76:77]
	v_cndmask_b32_e64 v76, v76, v128, s[76:77]
	s_waitcnt lgkmcnt(9)
	v_pk_add_f32 v[126:127], v[226:227], v[74:75]
	v_pk_add_f32 v[128:129], v[228:229], v[76:77]
	v_cndmask_b32_e64 v75, v75, v127, s[78:79]
	v_cndmask_b32_e64 v74, v74, v126, s[78:79]
	v_pk_add_f32 v[126:127], v[70:71], v[228:229]
	v_cndmask_b32_e64 v77, v77, v129, s[78:79]
	v_cndmask_b32_e64 v76, v76, v128, s[78:79]
	v_pk_add_f32 v[72:73], v[72:73], v[226:227]
	s_waitcnt lgkmcnt(8)
	v_pk_add_f32 v[66:67], v[230:231], v[74:75]
	v_pk_add_f32 v[128:129], v[232:233], v[76:77]
	v_cndmask_b32_e64 v75, v75, v67, s[80:81]
	v_cndmask_b32_e64 v74, v74, v66, s[80:81]
	v_pk_add_f32 v[66:67], v[126:127], v[232:233]
	v_pk_add_f32 v[68:69], v[72:73], v[230:231]
	v_cndmask_b32_e64 v77, v77, v129, s[80:81]
	v_cndmask_b32_e64 v76, v76, v128, s[80:81]
	v_mul_f32_e32 v16, 0x3fb8aa3b, v68
	v_mul_f32_e32 v119, 0x3fb8aa3b, v66
	s_waitcnt lgkmcnt(7)
	v_pk_add_f32 v[126:127], v[234:235], v[74:75]
	v_pk_add_f32 v[128:129], v[236:237], v[76:77]
	v_cndmask_b32_e64 v75, v75, v127, s[82:83]
	v_cndmask_b32_e64 v74, v74, v126, s[82:83]
	v_cndmask_b32_e64 v77, v77, v129, s[82:83]
	v_cndmask_b32_e64 v76, v76, v128, s[82:83]
	v_pk_add_f32 v[126:127], v[66:67], v[236:237]
	v_pk_add_f32 v[128:129], v[68:69], v[234:235]
	v_exp_f32_e32 v16, v16
	v_exp_f32_e32 v119, v119
	s_waitcnt lgkmcnt(6)
	v_pk_add_f32 v[130:131], v[238:239], v[74:75]
	v_pk_add_f32 v[132:133], v[240:241], v[76:77]
	v_pk_add_f32 v[126:127], v[126:127], v[240:241]
	v_pk_add_f32 v[128:129], v[128:129], v[238:239]
	v_cndmask_b32_e64 v75, v75, v131, s[84:85]
	v_cndmask_b32_e64 v74, v74, v130, s[84:85]
	v_cndmask_b32_e64 v77, v77, v133, s[84:85]
	v_cndmask_b32_e64 v76, v76, v132, s[84:85]
	s_waitcnt lgkmcnt(5)
	v_pk_add_f32 v[130:131], v[242:243], v[74:75]
	v_pk_add_f32 v[132:133], v[244:245], v[76:77]
	v_pk_add_f32 v[126:127], v[126:127], v[244:245]
	v_pk_add_f32 v[128:129], v[128:129], v[242:243]
	v_cndmask_b32_e64 v75, v75, v131, s[86:87]
	v_cndmask_b32_e64 v74, v74, v130, s[86:87]
	v_cndmask_b32_e64 v77, v77, v133, s[86:87]
	v_cndmask_b32_e64 v76, v76, v132, s[86:87]
	s_waitcnt lgkmcnt(4)
; __device__ __forceinline__ unsigned cvt_pk_bf16(float lo, float hi) { unsigned r; asm("v_cvt_pk_bf16_f32 %0, %1, %2" : "=v"(r) : "v"(lo), "v"(hi)); return r; }
; __device__ __forceinline__ void hg_block(ArgsP a_, int jl, unsigned char* smem) { const ArgsP a = a_;
;     ...
;           float ktv[4][4];
; #pragma unroll
;           for (int r = 0; r < 4; ++r) { const int i = 4 * rg + r; const f32x4 d = pre + cs[r] - gmid;
;               const f32x4 q = {__uint_as_float(q2[r].x << 16), __uint_as_float(q2[r].x & 0xffff0000u), __uint_as_float(q2[r].y << 16), __uint_as_float(q2[r].y & 0xffff0000u)};
;               const f32x4 kk = {__uint_as_float(kk2[r].x << 16), __uint_as_float(kk2[r].x & 0xffff0000u), __uint_as_float(kk2[r].y << 16), __uint_as_float(kk2[r].y & 0xffff0000u)};
;               f32x4 qa, qs, kb;
; #pragma unroll
;               for (int e = 0; e < 4; ++e) { const float eq = __expf(d[e]), ek = __expf(-d[e]); qa[e] = q[e] * eq; qs[e] = qa[e] * Emid[e]; kb[e] = kk[e] * ek; ktv[r][e] = kb[e] * Elm[e]; }
;               *(u32x2*)(QA + i * LQ + c4) = (u32x2){cvt_pk_bf16(qa[0], qa[1]), cvt_pk_bf16(qa[2], qa[3])};
;               *(u32x2*)(QS + i * LQ + c4) = (u32x2){cvt_pk_bf16(qs[0], qs[1]), cvt_pk_bf16(qs[2], qs[3])};
;               *(u32x2*)(KB + i * LQ + c4) = (u32x2){cvt_pk_bf16(kb[0], kb[1]), cvt_pk_bf16(kb[2], kb[3])}; }
	v_pk_add_f32 v[130:131], v[246:247], v[74:75]
	v_pk_add_f32 v[132:133], v[248:249], v[76:77]
	v_pk_add_f32 v[126:127], v[126:127], v[248:249]
	v_pk_add_f32 v[128:129], v[128:129], v[246:247]
	v_cndmask_b32_e64 v75, v75, v131, s[88:89]
	v_cndmask_b32_e64 v74, v74, v130, s[88:89]
	v_cndmask_b32_e64 v77, v77, v133, s[88:89]
	v_cndmask_b32_e64 v76, v76, v132, s[88:89]
	s_waitcnt lgkmcnt(3)
	v_pk_add_f32 v[130:131], v[202:203], v[74:75]
	v_pk_add_f32 v[132:133], v[204:205], v[76:77]
	v_pk_add_f32 v[126:127], v[126:127], v[204:205]
	v_pk_add_f32 v[128:129], v[128:129], v[202:203]
	v_cndmask_b32_e64 v75, v75, v131, s[90:91]
	v_cndmask_b32_e64 v74, v74, v130, s[90:91]
	v_cndmask_b32_e64 v77, v77, v133, s[90:91]
	v_cndmask_b32_e64 v76, v76, v132, s[90:91]
	s_waitcnt lgkmcnt(2)
	v_pk_add_f32 v[130:131], v[206:207], v[74:75]
	v_pk_add_f32 v[132:133], v[208:209], v[76:77]
	v_pk_add_f32 v[126:127], v[126:127], v[208:209]
	v_pk_add_f32 v[128:129], v[128:129], v[206:207]
	v_cndmask_b32_e64 v75, v75, v131, s[92:93]
	v_cndmask_b32_e64 v74, v74, v130, s[92:93]
	v_cndmask_b32_e64 v77, v77, v133, s[92:93]
	v_cndmask_b32_e64 v76, v76, v132, s[92:93]
	s_waitcnt lgkmcnt(1)
	v_pk_add_f32 v[130:131], v[210:211], v[74:75]
	v_pk_add_f32 v[132:133], v[212:213], v[76:77]
	v_cndmask_b32_e64 v131, v75, v131, s[94:95]
	v_cndmask_b32_e64 v130, v74, v130, s[94:95]
	v_pk_add_f32 v[126:127], v[126:127], v[212:213]
	v_cndmask_b32_e64 v77, v77, v133, s[94:95]
	v_cndmask_b32_e64 v76, v76, v132, s[94:95]
	v_pk_add_f32 v[128:129], v[128:129], v[210:211]
	s_waitcnt lgkmcnt(0)
	v_pk_add_f32 v[132:133], v[214:215], v[130:131]
	v_pk_add_f32 v[72:73], v[128:129], v[214:215]
	v_cndmask_b32_e64 v129, v130, v132, s[96:97]
	v_add_f32_e32 v64, v64, v129
	v_sub_f32_e32 v64, v64, v68
	v_mul_f32_e32 v179, 0x3fb8aa3b, v64
	v_mul_f32_e32 v64, 0xbfb8aa3b, v64
	v_exp_f32_e32 v64, v64
	v_cndmask_b32_e64 v128, v131, v133, s[96:97]
	v_pk_add_f32 v[176:177], v[216:217], v[76:77]
	v_pk_add_f32 v[70:71], v[126:127], v[216:217]
	v_mul_f32_e32 v175, v64, v175
	v_add_f32_e32 v64, v65, v128
	v_sub_f32_e32 v64, v64, v69
	v_mul_f32_e32 v65, 0x3fb8aa3b, v64
	v_mul_f32_e32 v64, 0xbfb8aa3b, v64
	v_exp_f32_e32 v64, v64
	v_cndmask_b32_e64 v76, v76, v176, s[96:97]
	v_add_f32_e32 v62, v62, v76
	v_and_b32_e32 v176, 0xffff0000, v78
	v_sub_f32_e32 v62, v62, v66
	v_mul_f32_e32 v176, v64, v176
	v_mul_f32_e32 v64, 0x3fb8aa3b, v62
	v_mul_f32_e32 v62, 0xbfb8aa3b, v62
	v_exp_f32_e32 v62, v62
	v_cndmask_b32_e64 v77, v77, v177, s[96:97]
	v_lshlrev_b32_e32 v177, 16, v79
	v_sub_f32_e32 v74, v72, v68
	v_mul_f32_e32 v177, v62, v177
	v_add_f32_e32 v62, v63, v77
	v_sub_f32_e32 v62, v62, v67
	v_mul_f32_e32 v63, 0x3fb8aa3b, v62
	v_mul_f32_e32 v75, 0x3fb8aa3b, v69
	v_mul_f32_e32 v126, 0x3fb8aa3b, v67
	v_exp_f32_e32 v179, v179
	v_exp_f32_e32 v65, v65
	v_exp_f32_e32 v64, v64
	v_exp_f32_e32 v63, v63
	v_mul_f32_e32 v74, 0x3fb8aa3b, v74
	v_exp_f32_e32 v75, v75
	v_exp_f32_e32 v126, v126
	v_mul_f32_e32 v62, 0xbfb8aa3b, v62
	v_exp_f32_e32 v74, v74
	v_exp_f32_e32 v62, v62
	v_lshlrev_b32_e32 v130, 16, v80
	v_and_b32_e32 v131, 0xffff0000, v80
	v_lshlrev_b32_e32 v132, 16, v81
	v_and_b32_e32 v133, 0xffff0000, v81
	v_mul_f32_e32 v130, v179, v130
	v_mul_f32_e32 v65, v65, v131
	v_mul_f32_e32 v64, v64, v132
	v_mul_f32_e32 v63, v63, v133
	v_add_f32_e32 v60, v60, v129
	v_mul_f32_e32 v179, v16, v130
	v_mul_f32_e32 v131, v75, v65
	v_mul_f32_e32 v132, v119, v64
	v_mul_f32_e32 v133, v126, v63
	v_cvt_pk_bf16_f32 v63, v64, v63
	v_cvt_pk_bf16_f32 v64, v179, v131
	v_sub_f32_e32 v60, v60, v68
	v_mul_f32_e32 v180, v74, v175
	v_mul_f32_e32 v178, v62, v178
	v_cvt_pk_bf16_f32 v62, v130, v65
	v_cvt_pk_bf16_f32 v65, v132, v133
	ds_write_b64 v106, v[64:65] offset:34816
	v_cvt_pk_bf16_f32 v64, v175, v176
	v_mul_f32_e32 v175, 0x3fb8aa3b, v60
	v_mul_f32_e32 v60, 0xbfb8aa3b, v60
	v_exp_f32_e32 v60, v60
	v_lshlrev_b32_e32 v130, 16, v86
	v_add_f32_e32 v58, v58, v76
	v_and_b32_e32 v131, 0xffff0000, v86
	v_mul_f32_e32 v130, v60, v130
	v_add_f32_e32 v60, v61, v128
	v_sub_f32_e32 v60, v60, v69
	v_mul_f32_e32 v61, 0x3fb8aa3b, v60
	v_mul_f32_e32 v60, 0xbfb8aa3b, v60
	v_exp_f32_e32 v60, v60
	v_sub_f32_e32 v58, v58, v66
	v_lshlrev_b32_e32 v132, 16, v87
	v_sub_f32_e32 v117, v73, v69
	v_mul_f32_e32 v131, v60, v131
	v_mul_f32_e32 v60, 0x3fb8aa3b, v58
	v_mul_f32_e32 v58, 0xbfb8aa3b, v58
	v_exp_f32_e32 v58, v58
	v_exp_f32_e32 v175, v175
	v_exp_f32_e32 v61, v61
	v_exp_f32_e32 v60, v60
	v_mul_f32_e32 v132, v58, v132
	v_add_f32_e32 v58, v59, v77
	v_sub_f32_e32 v58, v58, v67
	v_mul_f32_e32 v59, 0x3fb8aa3b, v58
	v_exp_f32_e32 v59, v59
	v_mul_f32_e32 v117, 0x3fb8aa3b, v117
	v_mul_f32_e32 v58, 0xbfb8aa3b, v58
	v_exp_f32_e32 v117, v117
	v_cvt_pk_bf16_f32 v65, v177, v178
	v_exp_f32_e32 v58, v58
	ds_write2st64_b64 v106, v[62:63], v[64:65] offset1:34
	v_lshlrev_b32_e32 v62, 16, v88
	v_and_b32_e32 v63, 0xffff0000, v88
	v_lshlrev_b32_e32 v64, 16, v89
	v_and_b32_e32 v65, 0xffff0000, v89
	v_mul_f32_e32 v62, v175, v62
	v_mul_f32_e32 v61, v61, v63
	v_mul_f32_e32 v60, v60, v64
	v_mul_f32_e32 v59, v59, v65
	v_add_f32_e32 v56, v56, v129
	v_and_b32_e32 v133, 0xffff0000, v87
	v_mul_f32_e32 v175, v16, v62
	v_mul_f32_e32 v63, v75, v61
	v_mul_f32_e32 v64, v119, v60
	v_mul_f32_e32 v65, v126, v59
	v_cvt_pk_bf16_f32 v59, v60, v59
	v_cvt_pk_bf16_f32 v60, v175, v63
	v_sub_f32_e32 v56, v56, v68
	v_mul_f32_e32 v181, v117, v176
	v_mul_f32_e32 v176, v74, v130
	v_mul_f32_e32 v133, v58, v133
	v_cvt_pk_bf16_f32 v58, v62, v61
	v_cvt_pk_bf16_f32 v61, v64, v65
; __device__ __forceinline__ unsigned cvt_pk_bf16(float lo, float hi) { unsigned r; asm("v_cvt_pk_bf16_f32 %0, %1, %2" : "=v"(r) : "v"(lo), "v"(hi)); return r; }
; __device__ __forceinline__ void hg_block(ArgsP a_, int jl, unsigned char* smem) { const ArgsP a = a_;
;     ...
;           for (int r = 0; r < 4; ++r) { const int i = 4 * rg + r; const f32x4 d = pre + cs[r] - gmid;
;               const f32x4 q = {__uint_as_float(q2[r].x << 16), __uint_as_float(q2[r].x & 0xffff0000u), __uint_as_float(q2[r].y << 16), __uint_as_float(q2[r].y & 0xffff0000u)};
;               const f32x4 kk = {__uint_as_float(kk2[r].x << 16), __uint_as_float(kk2[r].x & 0xffff0000u), __uint_as_float(kk2[r].y << 16), __uint_as_float(kk2[r].y & 0xffff0000u)};
;               f32x4 qa, qs, kb;
; #pragma unroll
;               for (int e = 0; e < 4; ++e) { const float eq = __expf(d[e]), ek = __expf(-d[e]); qa[e] = q[e] * eq; qs[e] = qa[e] * Emid[e]; kb[e] = kk[e] * ek; ktv[r][e] = kb[e] * Elm[e]; }
;               *(u32x2*)(QA + i * LQ + c4) = (u32x2){cvt_pk_bf16(qa[0], qa[1]), cvt_pk_bf16(qa[2], qa[3])};
;               *(u32x2*)(QS + i * LQ + c4) = (u32x2){cvt_pk_bf16(qs[0], qs[1]), cvt_pk_bf16(qs[2], qs[3])};
;               *(u32x2*)(KB + i * LQ + c4) = (u32x2){cvt_pk_bf16(kb[0], kb[1]), cvt_pk_bf16(kb[2], kb[3])}; }
; #pragma unroll
;           for (int e = 0; e < 4; ++e) {
;               *(u32x2*)(KT + (c4 + e) * LJ + 4 * rg) = (u32x2){cvt_pk_bf16(ktv[0][e], ktv[1][e]), cvt_pk_bf16(ktv[2][e], ktv[3][e])};
;               unsigned vv[4];
; #pragma unroll
;               for (int r = 0; r < 4; ++r) { const unsigned w = (e < 2) ? v2[r].x : v2[r].y; vv[r] = (e & 1) ? (w >> 16) : (w & 0xffffu); }
;               *(u32x2*)(VT + (c4 + e) * LJ + 4 * rg) = (u32x2){vv[0] | (vv[1] << 16), vv[2] | (vv[3] << 16)}; }
;           if (rg == 0) { f32x4 sd;
; #pragma unroll
;               for (int e = 0; e < 4; ++e) sd[e] = __expf(glast[e]);
;               *(f32x4*)(SDEC + c4) = sd; } }
	ds_write_b64 v108, v[60:61] offset:34816
	v_cvt_pk_bf16_f32 v60, v130, v131
	v_mul_f32_e32 v130, 0x3fb8aa3b, v56
	v_mul_f32_e32 v56, 0xbfb8aa3b, v56
	v_exp_f32_e32 v56, v56
	v_lshlrev_b32_e32 v62, 16, v98
	v_add_f32_e32 v54, v54, v76
	v_and_b32_e32 v63, 0xffff0000, v98
	v_mul_f32_e32 v62, v56, v62
	v_add_f32_e32 v56, v57, v128
	v_sub_f32_e32 v56, v56, v69
	v_mul_f32_e32 v57, 0x3fb8aa3b, v56
	v_mul_f32_e32 v56, 0xbfb8aa3b, v56
	v_exp_f32_e32 v56, v56
	v_sub_f32_e32 v54, v54, v66
	v_lshlrev_b32_e32 v64, 16, v99
	v_sub_f32_e32 v123, v70, v66
	v_mul_f32_e32 v63, v56, v63
	v_mul_f32_e32 v56, 0x3fb8aa3b, v54
	v_mul_f32_e32 v54, 0xbfb8aa3b, v54
	v_exp_f32_e32 v54, v54
	v_exp_f32_e32 v130, v130
	v_exp_f32_e32 v57, v57
	v_exp_f32_e32 v56, v56
	v_mul_f32_e32 v64, v54, v64
	v_add_f32_e32 v54, v55, v77
	v_sub_f32_e32 v54, v54, v67
	v_mul_f32_e32 v55, 0x3fb8aa3b, v54
	v_exp_f32_e32 v55, v55
	v_mul_f32_e32 v123, 0x3fb8aa3b, v123
	v_mul_f32_e32 v54, 0xbfb8aa3b, v54
	v_exp_f32_e32 v123, v123
	v_cvt_pk_bf16_f32 v61, v132, v133
	v_exp_f32_e32 v54, v54
	ds_write2st64_b64 v108, v[58:59], v[60:61] offset1:34
	v_lshlrev_b32_e32 v58, 16, v100
	v_and_b32_e32 v59, 0xffff0000, v100
	v_lshlrev_b32_e32 v60, 16, v101
	v_and_b32_e32 v61, 0xffff0000, v101
	v_mul_f32_e32 v58, v130, v58
	v_mul_f32_e32 v57, v57, v59
	v_mul_f32_e32 v56, v56, v60
	v_mul_f32_e32 v55, v55, v61
	v_add_f32_e32 v50, v50, v129
	v_and_b32_e32 v65, 0xffff0000, v99
	v_mul_f32_e32 v130, v16, v58
	v_mul_f32_e32 v59, v75, v57
	v_mul_f32_e32 v60, v119, v56
	v_mul_f32_e32 v61, v126, v55
	v_cvt_pk_bf16_f32 v55, v56, v55
	v_cvt_pk_bf16_f32 v56, v130, v59
	v_sub_f32_e32 v50, v50, v68
	v_mul_f32_e32 v182, v123, v177
	v_mul_f32_e32 v177, v117, v131
	v_mul_f32_e32 v131, v74, v62
	v_mul_f32_e32 v65, v54, v65
	v_cvt_pk_bf16_f32 v54, v58, v57
	v_cvt_pk_bf16_f32 v57, v60, v61
	ds_write_b64 v147, v[56:57] offset:34816
	v_cvt_pk_bf16_f32 v56, v62, v63
	v_mul_f32_e32 v62, 0x3fb8aa3b, v50
	v_mul_f32_e32 v50, 0xbfb8aa3b, v50
	v_exp_f32_e32 v50, v50
	v_lshlrev_b32_e32 v58, 16, v110
	v_and_b32_e32 v59, 0xffff0000, v110
	v_lshlrev_b32_e32 v60, 16, v111
	v_mul_f32_e32 v58, v50, v58
	v_add_f32_e32 v50, v51, v128
	v_sub_f32_e32 v50, v50, v69
	v_mul_f32_e32 v51, 0x3fb8aa3b, v50
	v_mul_f32_e32 v50, 0xbfb8aa3b, v50
	v_exp_f32_e32 v50, v50
	v_exp_f32_e32 v62, v62
	v_exp_f32_e32 v51, v51
	v_sub_f32_e32 v127, v71, v67
	v_mul_f32_e32 v59, v50, v59
	v_add_f32_e32 v50, v52, v76
	v_sub_f32_e32 v50, v50, v66
	v_mul_f32_e32 v52, 0x3fb8aa3b, v50
	v_mul_f32_e32 v50, 0xbfb8aa3b, v50
	v_exp_f32_e32 v50, v50
	v_exp_f32_e32 v52, v52
	v_mul_f32_e32 v127, 0x3fb8aa3b, v127
	v_cvt_pk_bf16_f32 v57, v64, v65
	v_mul_f32_e32 v60, v50, v60
	v_add_f32_e32 v50, v53, v77
	v_sub_f32_e32 v50, v50, v67
	v_mul_f32_e32 v53, 0x3fb8aa3b, v50
	v_mul_f32_e32 v50, 0xbfb8aa3b, v50
	v_exp_f32_e32 v53, v53
	v_exp_f32_e32 v50, v50
	ds_write2st64_b64 v147, v[54:55], v[56:57] offset1:34
	v_lshlrev_b32_e32 v54, 16, v112
	v_and_b32_e32 v55, 0xffff0000, v112
	v_lshlrev_b32_e32 v56, 16, v113
	v_exp_f32_e32 v127, v127
	v_and_b32_e32 v57, 0xffff0000, v113
	v_and_b32_e32 v61, 0xffff0000, v111
	v_mul_f32_e32 v54, v62, v54
	v_mul_f32_e32 v51, v51, v55
	v_mul_f32_e32 v52, v52, v56
	v_mul_f32_e32 v16, v16, v54
	v_mul_f32_e32 v55, v75, v51
	v_mul_f32_e32 v56, v119, v52
	v_mul_f32_e32 v53, v53, v57
	v_mul_f32_e32 v61, v50, v61
	v_cvt_pk_bf16_f32 v50, v54, v51
	v_cvt_pk_bf16_f32 v51, v52, v53
	v_cvt_pk_bf16_f32 v52, v16, v55
	v_mul_f32_e32 v57, v126, v53
	v_cvt_pk_bf16_f32 v53, v56, v57
	ds_write_b64 v165, v[52:53] offset:34816
	v_cvt_pk_bf16_f32 v52, v58, v59
	v_and_b32_e32 v16, 0xffff, v82
	v_mul_f32_e32 v62, v74, v58
	v_cvt_pk_bf16_f32 v53, v60, v61
	ds_write2st64_b64 v165, v[50:51], v[52:53] offset1:34
	v_cvt_pk_bf16_f32 v50, v180, v176
	v_cvt_pk_bf16_f32 v51, v131, v62
	v_lshl_or_b32 v52, v90, 16, v16
	v_add_u32_e32 v16, 0xc800, v166
	v_mul_f32_e32 v183, v127, v178
	v_mul_f32_e32 v178, v123, v132
	v_mul_f32_e32 v132, v117, v63
	v_mul_f32_e32 v63, v117, v59
	v_and_b32_e32 v53, 0xffff, v102
	v_cvt_pk_bf16_f32 v54, v181, v177
	v_cvt_pk_bf16_f32 v55, v132, v63
	ds_write2_b64 v16, v[50:51], v[54:55] offset0:128 offset1:146
	v_lshrrev_b32_e32 v50, 16, v82
	v_lshrrev_b32_e32 v51, 16, v102
	v_lshl_or_b32 v53, v120, 16, v53
	v_and_or_b32 v50, v90, s49, v50
	v_and_or_b32 v51, v120, s49, v51
	v_mul_f32_e32 v179, v127, v133
	v_mul_f32_e32 v133, v123, v64
	v_mul_f32_e32 v64, v123, v60
	ds_write2_b64 v167, v[52:53], v[50:51] offset1:18
	v_cvt_pk_bf16_f32 v51, v133, v64
	v_mul_f32_e32 v175, v127, v65
	v_mul_f32_e32 v65, v127, v61
	v_cvt_pk_bf16_f32 v50, v182, v178
	v_and_b32_e32 v52, 0xffff, v83
	v_and_b32_e32 v53, 0xffff, v103
	v_cvt_pk_bf16_f32 v54, v183, v179
	v_cvt_pk_bf16_f32 v55, v175, v65
	ds_write2_b64 v16, v[50:51], v[54:55] offset0:164 offset1:182
	v_lshrrev_b32_e32 v16, 16, v83
	v_lshrrev_b32_e32 v51, 16, v103
	v_lshl_or_b32 v52, v91, 16, v52
	v_lshl_or_b32 v53, v121, 16, v53
	v_and_or_b32 v50, v91, s49, v16
	v_and_or_b32 v51, v121, s49, v51
	ds_write2_b64 v167, v[52:53], v[50:51] offset0:36 offset1:54
	s_mov_b64 s[52:53], exec
	v_readlane_b32 s54, v255, 12
	v_readlane_b32 s55, v255, 13
	s_and_b64 s[54:55], s[52:53], s[54:55]
	s_mov_b64 exec, s[54:55]
	s_cbranch_execz .LBB0_414
	v_mul_f32_e32 v16, 0x3fb8aa3b, v72
	v_exp_f32_e32 v50, v16
	v_mul_f32_e32 v16, 0x3fb8aa3b, v73
	v_exp_f32_e32 v51, v16
	v_mul_f32_e32 v16, 0x3fb8aa3b, v70
	v_exp_f32_e32 v52, v16
	v_mul_f32_e32 v16, 0x3fb8aa3b, v71
	v_exp_f32_e32 v53, v16
	ds_write_b128 v137, v[50:53]

; __device__ __forceinline__ void hg_block(ArgsP a_, int jl, unsigned char* smem) { const ArgsP a = a_;
;     ...
;         if (uu + 1 < ntot_) HG_LOAD(un_);
.LBB0_419:
	s_nop 0
	v_writelane_b32 v255, s55, 40
	s_lshl_b32 s52, s52, 7
	s_and_b32 s52, s52, 0x380
	v_or_b32_e32 v16, s52, v93
	v_mov_b32_e32 v117, v17
	v_mov_b32_e32 v119, v17
	v_add_u32_e32 v202, s54, v136
	v_ashrrev_i32_e32 v203, 31, v202
	v_lshlrev_b64 v[202:203], 10, v[202:203]
	v_or_b32_e32 v202, v202, v16
	v_lshl_add_u64 v[204:205], v[202:203], 2, s[34:35]
	global_load_dwordx4 v[0:3], v[204:205], off
	v_lshlrev_b64 v[202:203], 1, v[202:203]
	v_lshl_add_u64 v[204:205], s[18:19], 0, v[202:203]
	global_load_dwordx2 v[82:83], v[204:205], off
	v_lshl_add_u64 v[204:205], s[22:23], 0, v[202:203]
	global_load_dwordx2 v[78:79], v[204:205], off
	v_lshl_add_u64 v[204:205], s[26:27], 0, v[202:203]
	global_load_dwordx2 v[80:81], v[204:205], off
	v_add_u32_e32 v202, s54, v107
	v_ashrrev_i32_e32 v203, 31, v202
	v_lshlrev_b64 v[202:203], 10, v[202:203]
	v_or_b32_e32 v202, v202, v16
	v_lshl_add_u64 v[204:205], v[202:203], 2, s[34:35]
	global_load_dwordx4 v[4:7], v[204:205], off
	v_lshlrev_b64 v[202:203], 1, v[202:203]
	v_lshl_add_u64 v[204:205], s[18:19], 0, v[202:203]
	global_load_dwordx2 v[90:91], v[204:205], off
	v_lshl_add_u64 v[204:205], s[22:23], 0, v[202:203]
	global_load_dwordx2 v[86:87], v[204:205], off
	v_lshl_add_u64 v[204:205], s[26:27], 0, v[202:203]
	global_load_dwordx2 v[88:89], v[204:205], off
	v_add_u32_e32 v202, s54, v109
	v_ashrrev_i32_e32 v203, 31, v202
	v_lshlrev_b64 v[202:203], 10, v[202:203]
	v_or_b32_e32 v202, v202, v16
	v_lshl_add_u64 v[204:205], v[202:203], 2, s[34:35]
	global_load_dwordx4 v[8:11], v[204:205], off
	v_lshlrev_b64 v[202:203], 1, v[202:203]
	v_lshl_add_u64 v[204:205], s[18:19], 0, v[202:203]
	global_load_dwordx2 v[102:103], v[204:205], off
	v_lshl_add_u64 v[204:205], s[22:23], 0, v[202:203]
	global_load_dwordx2 v[98:99], v[204:205], off
	v_lshl_add_u64 v[204:205], s[26:27], 0, v[202:203]
	global_load_dwordx2 v[100:101], v[204:205], off
	v_add_u32_e32 v202, s54, v164
	v_ashrrev_i32_e32 v203, 31, v202
	v_lshlrev_b64 v[202:203], 10, v[202:203]
	v_or_b32_e32 v202, v202, v16
	v_lshl_add_u64 v[204:205], v[202:203], 2, s[34:35]
	global_load_dwordx4 v[12:15], v[204:205], off
	v_lshlrev_b64 v[202:203], 1, v[202:203]
	v_lshl_add_u64 v[204:205], s[18:19], 0, v[202:203]
	global_load_dwordx2 v[120:121], v[204:205], off
	v_lshl_add_u64 v[204:205], s[22:23], 0, v[202:203]
	global_load_dwordx2 v[110:111], v[204:205], off
	v_lshl_add_u64 v[204:205], s[26:27], 0, v[202:203]
	global_load_dwordx2 v[112:113], v[204:205], off
	s_lshl_b32 s52, s52, 1
	s_mov_b32 s53, s12
	v_add_u32_e32 v50, s54, v134
	v_ashrrev_i32_e32 v51, 31, v50
	v_readlane_b32 s54, v255, 6
	v_lshlrev_b64 v[50:51], 11, v[50:51]
	v_readlane_b32 s55, v255, 7
	s_nop 1
	v_lshl_add_u64 v[50:51], s[54:55], 0, v[50:51]
	v_lshl_add_u64 v[50:51], v[50:51], 0, s[52:53]
	v_lshl_add_u64 v[50:51], v[50:51], 0, v[116:117]
	v_lshl_add_u64 v[50:51], v[50:51], 0, v[118:119]
	global_load_dwordx2 v[132:133], v[50:51], off
	global_load_dwordx2 v[130:131], v[50:51], off offset:32
	global_load_dwordx2 v[128:129], v[50:51], off offset:64
	global_load_dwordx2 v[126:127], v[50:51], off offset:96

; __device__ __forceinline__ unsigned cvt_pk_bf16(float lo, float hi) { unsigned r; asm("v_cvt_pk_bf16_f32 %0, %1, %2" : "=v"(r) : "v"(lo), "v"(hi)); return r; }
; __device__ __forceinline__ void hg_block(ArgsP a_, int jl, unsigned char* smem) { const ArgsP a = a_;
;     ...
;         { f32x4 run = {0.f, 0.f, 0.f, 0.f};
; #pragma unroll
;           for (int r = 0; r < 4; ++r) { run = run + lf4[r]; cs[r] = run; }
;           *(f32x4*)(TOT + rg * 128 + c4) = run; }
;     ...
;         __syncthreads();
;         if (irow < len) { const float rstd = rsqrtf((RSm[irow * 2] + RSm[irow * 2 + 1]) * (1.f / 128.f) + LN_EPS);
; #pragma unroll
;             for (int vt = 0; vt < 4; ++vt) { const int v = 16 * (hw * 4 + vt) + 4 * fq; const size_t o = (size_t)(row0 + irow) * 1024 + h * 128 + v;
;                 const f32x4 gg = *(const f32x4*)(ng + h * 128 + v); const u32x2 gt = gcur[vt];
;                 const float g0 = __uint_as_float(gt.x << 16), g1 = __uint_as_float(gt.x & 0xffff0000u), g2 = __uint_as_float(gt.y << 16), g3 = __uint_as_float(gt.y & 0xffff0000u);
;                 u32x2 w; w.x = cvt_pk_bf16(O[vt][0] * rstd * gg[0] * g0, O[vt][1] * rstd * gg[1] * g1); w.y = cvt_pk_bf16(O[vt][2] * rstd * gg[2] * g2, O[vt][3] * rstd * gg[3] * g3);
;                 *(u32x2*)(ON + o) = w; } }
.LBB0_438:
	s_or_b64 exec, exec, s[52:53]
	s_waitcnt vmcnt(0)
	v_readlane_b32 s98, v255, 40
	s_nop 1
	s_cmp_eq_u32 s98, 64
	s_cbranch_scc1 .Lhg_etot_nomask
	v_cmp_gt_i32_e32 vcc, s98, v136
	s_nop 1
	v_cndmask_b32_e32 v0, 0, v0, vcc
	v_cndmask_b32_e32 v1, 0, v1, vcc
	v_cndmask_b32_e32 v2, 0, v2, vcc
	v_cndmask_b32_e32 v3, 0, v3, vcc
	v_cmp_gt_i32_e32 vcc, s98, v107
	s_nop 1
	v_cndmask_b32_e32 v4, 0, v4, vcc
	v_cndmask_b32_e32 v5, 0, v5, vcc
	v_cndmask_b32_e32 v6, 0, v6, vcc
	v_cndmask_b32_e32 v7, 0, v7, vcc
	v_cmp_gt_i32_e32 vcc, s98, v109
	s_nop 1
	v_cndmask_b32_e32 v8, 0, v8, vcc
	v_cndmask_b32_e32 v9, 0, v9, vcc
	v_cndmask_b32_e32 v10, 0, v10, vcc
	v_cndmask_b32_e32 v11, 0, v11, vcc
	v_cmp_gt_i32_e32 vcc, s98, v164
	s_nop 1
	v_cndmask_b32_e32 v12, 0, v12, vcc
	v_cndmask_b32_e32 v13, 0, v13, vcc
	v_cndmask_b32_e32 v14, 0, v14, vcc
	v_cndmask_b32_e32 v15, 0, v15, vcc
.Lhg_etot_nomask:
	v_pk_add_f32 v[240:241], v[0:1], 0 op_sel_hi:[1,0]
	v_pk_add_f32 v[242:243], v[2:3], 0 op_sel_hi:[1,0]
	v_pk_add_f32 v[240:241], v[240:241], v[4:5]
	v_pk_add_f32 v[242:243], v[242:243], v[6:7]
	v_pk_add_f32 v[240:241], v[240:241], v[8:9]
	v_pk_add_f32 v[242:243], v[242:243], v[10:11]
	v_pk_add_f32 v[240:241], v[240:241], v[12:13]
	v_pk_add_f32 v[242:243], v[242:243], v[14:15]
	ds_write_b128 v168, v[240:243]
	v_cmp_gt_i32_e32 vcc, s64, v134
	s_waitcnt lgkmcnt(0)
	s_barrier
	s_and_saveexec_b64 s[52:53], vcc
	s_cbranch_execz .LBB0_440
	v_add_u32_e32 v16, 0, v145
	v_add_u32_e32 v16, 0x22b00, v16
	ds_read_b64 v[66:67], v16
	s_lshl_b32 s54, s62, 8
	v_readlane_b32 s55, v255, 8
	s_add_u32 s54, s55, s54
	v_readlane_b32 s55, v255, 9
	s_waitcnt lgkmcnt(0)
	v_add_f32_e32 v16, v66, v67
	v_fmamk_f32 v16, v16, 0x3c000000, v187
	v_cmp_gt_f32_e32 vcc, s31, v16
	v_mul_f32_e32 v66, 0x4b800000, v16
	s_addc_u32 s55, s55, 0
	v_cndmask_b32_e32 v16, v16, v66, vcc
	v_rsq_f32_e32 v16, v16
	v_lshlrev_b32_e32 v74, 16, v124
	v_and_b32_e32 v75, 0xffff0000, v124
	v_lshlrev_b32_e32 v76, 16, v125
	v_mul_f32_e32 v66, 0x45800000, v16
	v_cndmask_b32_e32 v16, v16, v66, vcc
	v_add_u32_e32 v66, s63, v134
	v_ashrrev_i32_e32 v67, 31, v66
	v_lshlrev_b64 v[66:67], 11, v[66:67]
	v_lshl_add_u64 v[72:73], s[54:55], 0, v[66:67]
	s_lshl_b32 s54, s62, 9
	s_mov_b32 s55, s12
	v_lshl_add_u64 v[66:67], v[114:115], 0, s[54:55]
	v_mul_f32_e32 v62, v62, v16
	v_mul_f32_e32 v63, v63, v16
	v_and_b32_e32 v77, 0xffff0000, v125
	v_mov_b32_e32 v123, v17
	v_mul_f32_e32 v58, v58, v16
	v_mul_f32_e32 v59, v59, v16
	v_mul_f32_e32 v54, v54, v16
	v_mul_f32_e32 v55, v55, v16
	v_mul_f32_e32 v50, v50, v16
	v_mul_f32_e32 v51, v51, v16
	s_waitcnt vmcnt(0)
	v_mul_f32_e32 v62, v202, v62
	v_mul_f32_e32 v63, v203, v63
	v_mul_f32_e32 v62, v62, v74
	v_mul_f32_e32 v63, v63, v75
	v_cvt_pk_bf16_f32 v68, v62, v63
	v_mul_f32_e32 v62, v64, v16
	v_mul_f32_e32 v63, v65, v16
	v_mul_f32_e32 v62, v204, v62
	v_mul_f32_e32 v63, v205, v63
	v_mul_f32_e32 v62, v62, v76
	v_mul_f32_e32 v63, v63, v77
	v_cvt_pk_bf16_f32 v69, v62, v63
	v_lshl_add_u64 v[62:63], v[72:73], 0, v[122:123]
	global_store_dwordx2 v[62:63], v[68:69], off
	v_lshlrev_b32_e32 v64, 16, v104
	v_and_b32_e32 v65, 0xffff0000, v104
	v_lshlrev_b32_e32 v72, 16, v105
	v_and_b32_e32 v73, 0xffff0000, v105
	v_mul_f32_e32 v58, v206, v58
	v_mul_f32_e32 v59, v207, v59
	v_mul_f32_e32 v58, v58, v64
	v_mul_f32_e32 v59, v59, v65
	v_cvt_pk_bf16_f32 v58, v58, v59
	v_mul_f32_e32 v59, v60, v16
	v_mul_f32_e32 v59, v208, v59
	v_mul_f32_e32 v60, v61, v16
	v_mul_f32_e32 v59, v59, v72
	v_mul_f32_e32 v60, v209, v60
	v_mul_f32_e32 v60, v60, v73
	v_cvt_pk_bf16_f32 v59, v59, v60
	global_store_dwordx2 v[62:63], v[58:59], off offset:32
	v_lshlrev_b32_e32 v64, 16, v94
	v_and_b32_e32 v65, 0xffff0000, v94
	v_lshlrev_b32_e32 v68, 16, v95
	v_and_b32_e32 v69, 0xffff0000, v95
	v_mul_f32_e32 v54, v54, v210
	v_mul_f32_e32 v55, v55, v211
	v_mul_f32_e32 v54, v54, v64
	v_mul_f32_e32 v55, v55, v65
	v_cvt_pk_bf16_f32 v54, v54, v55
	v_mul_f32_e32 v55, v56, v16
	v_mul_f32_e32 v55, v55, v212
	v_mul_f32_e32 v56, v57, v16
	v_mul_f32_e32 v55, v55, v68
	v_mul_f32_e32 v56, v56, v213
	v_mul_f32_e32 v56, v56, v69
	v_cvt_pk_bf16_f32 v55, v55, v56
	global_store_dwordx2 v[62:63], v[54:55], off offset:64
	v_lshlrev_b32_e32 v58, 16, v84
	v_and_b32_e32 v59, 0xffff0000, v84
	v_lshlrev_b32_e32 v60, 16, v85
	v_and_b32_e32 v61, 0xffff0000, v85
	v_mul_f32_e32 v50, v50, v214
	v_mul_f32_e32 v51, v51, v215
	v_mul_f32_e32 v50, v50, v58
	v_mul_f32_e32 v51, v51, v59
	v_cvt_pk_bf16_f32 v50, v50, v51
	v_mul_f32_e32 v51, v52, v16
	v_mul_f32_e32 v51, v51, v216
	v_mul_f32_e32 v16, v53, v16
	v_mul_f32_e32 v51, v51, v60
	v_mul_f32_e32 v16, v16, v217
	v_mul_f32_e32 v16, v16, v61
	v_cvt_pk_bf16_f32 v51, v51, v16
	global_store_dwordx2 v[62:63], v[50:51], off offset:96
